# late-unit publish without L2 writeback: Epi2 and Epi3 result stores and the ssq atomics issued write-through (sc1), buffer_wbl2 removed from the SEAM3 and SEAM4 late paths
# speedup vs baseline: 1.0104x; 1.0056x over previous
.LBB0_635:
	v_lshl_add_u32 v148, s4, 8, v157
	s_cmpk_gt_i32 s4, 0xff
	v_readlane_b32 s60, v249, 1
	v_lshl_or_b32 v2, s56, 8, v168
	s_cselect_b64 s[56:57], -1, 0
	v_readlane_b32 s61, v249, 2
	v_ashrrev_i32_e32 v149, 31, v148
	s_and_b64 s[26:27], s[56:57], exec
	s_mov_b64 s[52:53], s[60:61]
	v_ashrrev_i32_e32 v3, 31, v2
	v_lshlrev_b64 v[150:151], 10, v[148:149]
	s_cselect_b32 s54, s44, s52
	s_cselect_b32 s55, s45, s53
	v_lshl_add_u64 v[150:151], v[150:151], 0, v[2:3]
	v_lshl_add_u64 v[154:155], v[150:151], 2, s[54:55]
	global_load_dwordx4 v[170:173], v[154:155], off
	global_load_dwordx4 v[174:177], v[154:155], off offset:16
	v_add_u32_e32 v1, s5, v167
	ds_read_b32 v152, v1 offset:4
	s_cmpk_lt_i32 s4, 0x100
	v_readlane_b32 s62, v249, 3
	v_readlane_b32 s63, v249, 4
	v_readlane_b32 s64, v249, 5
	v_readlane_b32 s65, v249, 6
	v_readlane_b32 s66, v249, 7
	v_readlane_b32 s67, v249, 8
	v_readlane_b32 s68, v249, 9
	v_readlane_b32 s69, v249, 10
	v_readlane_b32 s70, v249, 11
	v_readlane_b32 s71, v249, 12
	v_readlane_b32 s72, v249, 13
	v_readlane_b32 s73, v249, 14
	v_readlane_b32 s74, v249, 15
	v_readlane_b32 s75, v249, 16
	s_waitcnt vmcnt(0) lgkmcnt(0)
	v_pk_fma_f32 v[130:131], v[130:131], v[152:153], v[172:173] op_sel_hi:[1,0,1]
	v_pk_fma_f32 v[128:129], v[128:129], v[152:153], v[170:171] op_sel_hi:[1,0,1]
	v_pk_fma_f32 v[126:127], v[126:127], v[152:153], v[176:177] op_sel_hi:[1,0,1]
	v_pk_fma_f32 v[124:125], v[124:125], v[152:153], v[174:175] op_sel_hi:[1,0,1]
	s_cbranch_scc1 .LBB0_637
	v_lshl_add_u64 v[170:171], v[150:151], 2, s[28:29]
	global_store_dwordx4 v[170:171], v[128:131], off sc1
	global_store_dwordx4 v[170:171], v[124:127], off offset:16 sc1
.LBB0_637:
	v_lshl_add_u64 v[174:175], v[150:151], 1, s[10:11]
	v_cvt_pk_bf16_f32 v170, v128, v129
	v_cvt_pk_bf16_f32 v171, v130, v131
	v_cvt_pk_bf16_f32 v172, v124, v125
	v_cvt_pk_bf16_f32 v173, v126, v127
	global_store_dwordx4 v[174:175], v[170:173], off sc1
	global_load_dwordx4 v[170:173], v[154:155], off offset:512
	s_nop 0
	global_load_dwordx4 v[174:177], v[154:155], off offset:528
	v_mov_b32_e32 v153, v152
	v_mov_b32_e32 v154, v152
	v_mov_b32_e32 v155, v152
	v_cndmask_b32_e64 v178, 0, 1, s[56:57]
	v_cmp_ne_u32_e64 s[4:5], 1, v178
	s_andn2_b64 vcc, exec, s[56:57]
	s_waitcnt vmcnt(1)
	v_pk_fma_f32 v[122:123], v[122:123], v[154:155], v[172:173]
	v_pk_fma_f32 v[120:121], v[120:121], v[152:153], v[170:171]
	s_waitcnt vmcnt(0)
	v_pk_fma_f32 v[118:119], v[118:119], v[154:155], v[176:177]
	v_pk_fma_f32 v[116:117], v[116:117], v[152:153], v[174:175]
	s_cbranch_vccnz .LBB0_639
	v_lshl_add_u64 v[152:153], v[150:151], 2, s[28:29]
	global_store_dwordx4 v[152:153], v[120:123], off offset:512 sc1
	global_store_dwordx4 v[152:153], v[116:119], off offset:528 sc1
.LBB0_639:
	v_pk_mul_f32 v[126:127], v[126:127], v[126:127]
	v_pk_mul_f32 v[124:125], v[124:125], v[124:125]
	v_pk_fma_f32 v[130:131], v[130:131], v[130:131], v[126:127]
	v_pk_fma_f32 v[128:129], v[128:129], v[128:129], v[124:125]
	v_cvt_pk_bf16_f32 v124, v120, v121
	v_cvt_pk_bf16_f32 v125, v122, v123
	v_pk_fma_f32 v[122:123], v[122:123], v[122:123], v[130:131]
	v_pk_fma_f32 v[120:121], v[120:121], v[120:121], v[128:129]
	v_cvt_pk_bf16_f32 v126, v116, v117
	v_cvt_pk_bf16_f32 v127, v118, v119
	v_pk_fma_f32 v[118:119], v[118:119], v[118:119], v[122:123]
	v_pk_fma_f32 v[116:117], v[116:117], v[116:117], v[120:121]
	v_lshlrev_b64 v[150:151], 1, v[150:151]
	v_add_f32_e32 v116, v116, v117
	v_add_f32_e32 v117, v118, v119
	v_add_f32_e32 v116, v116, v117
	v_mov_b32_e32 v117, v116
	s_nop 1
	v_permlane16_swap_b32_e32 v116, v117
	v_add_f32_e32 v116, v116, v117
	v_or_b32_e32 v150, 0x100, v150
	v_mov_b32_e32 v117, v116
	v_lshl_add_u64 v[150:151], s[10:11], 0, v[150:151]
	s_nop 0
	v_permlane32_swap_b32_e32 v116, v117
	global_store_dwordx4 v[150:151], v[124:127], off sc1
	s_and_saveexec_b64 s[26:27], s[0:1]
	s_cbranch_execz .LBB0_641
	v_lshl_add_u64 v[118:119], v[148:149], 2, s[12:13]
	v_add_f32_e32 v116, v116, v117
	global_atomic_add_f32 v[118:119], v116, off sc1
.LBB0_641:
	s_or_b64 exec, exec, s[26:27]
	v_or_b32_e32 v116, 16, v148
	v_ashrrev_i32_e32 v117, 31, v116
	v_lshlrev_b64 v[118:119], 10, v[116:117]
	v_lshl_add_u64 v[118:119], v[118:119], 0, v[2:3]
	v_lshl_add_u64 v[122:123], v[118:119], 2, s[54:55]
	global_load_dwordx4 v[124:127], v[122:123], off
	global_load_dwordx4 v[128:131], v[122:123], off offset:16
	ds_read_b32 v120, v1 offset:132
	s_and_b64 vcc, exec, s[4:5]
	s_waitcnt vmcnt(1) lgkmcnt(0)
	v_pk_fma_f32 v[114:115], v[114:115], v[120:121], v[126:127] op_sel_hi:[1,0,1]
	v_pk_fma_f32 v[112:113], v[112:113], v[120:121], v[124:125] op_sel_hi:[1,0,1]
	s_waitcnt vmcnt(0)
	v_pk_fma_f32 v[110:111], v[110:111], v[120:121], v[130:131] op_sel_hi:[1,0,1]
	v_pk_fma_f32 v[108:109], v[108:109], v[120:121], v[128:129] op_sel_hi:[1,0,1]
	s_cbranch_vccnz .LBB0_643
	v_lshl_add_u64 v[124:125], v[118:119], 2, s[28:29]
	global_store_dwordx4 v[124:125], v[112:115], off sc1
	global_store_dwordx4 v[124:125], v[108:111], off offset:16 sc1
.LBB0_643:
	v_lshl_add_u64 v[128:129], v[118:119], 1, s[10:11]
	v_cvt_pk_bf16_f32 v124, v112, v113
	v_cvt_pk_bf16_f32 v125, v114, v115
	v_cvt_pk_bf16_f32 v126, v108, v109
	v_cvt_pk_bf16_f32 v127, v110, v111
	global_store_dwordx4 v[128:129], v[124:127], off sc1
	global_load_dwordx4 v[124:127], v[122:123], off offset:512
	s_nop 0
	global_load_dwordx4 v[128:131], v[122:123], off offset:528
	v_mov_b32_e32 v121, v120
	v_mov_b32_e32 v122, v120
	v_mov_b32_e32 v123, v120
	s_and_b64 vcc, exec, s[4:5]
	s_waitcnt vmcnt(1)
	v_pk_fma_f32 v[106:107], v[106:107], v[122:123], v[126:127]
	v_pk_fma_f32 v[104:105], v[104:105], v[120:121], v[124:125]
	s_waitcnt vmcnt(0)
	v_pk_fma_f32 v[102:103], v[102:103], v[122:123], v[130:131]
	v_pk_fma_f32 v[100:101], v[100:101], v[120:121], v[128:129]
	s_cbranch_vccnz .LBB0_645
	v_lshl_add_u64 v[120:121], v[118:119], 2, s[28:29]
	global_store_dwordx4 v[120:121], v[104:107], off offset:512 sc1
	global_store_dwordx4 v[120:121], v[100:103], off offset:528 sc1
.LBB0_645:
	v_pk_mul_f32 v[110:111], v[110:111], v[110:111]
	v_pk_mul_f32 v[108:109], v[108:109], v[108:109]
	v_pk_fma_f32 v[114:115], v[114:115], v[114:115], v[110:111]
	v_pk_fma_f32 v[112:113], v[112:113], v[112:113], v[108:109]
	v_cvt_pk_bf16_f32 v108, v104, v105
	v_cvt_pk_bf16_f32 v109, v106, v107
	v_pk_fma_f32 v[106:107], v[106:107], v[106:107], v[114:115]
	v_pk_fma_f32 v[104:105], v[104:105], v[104:105], v[112:113]
	v_cvt_pk_bf16_f32 v110, v100, v101
	v_cvt_pk_bf16_f32 v111, v102, v103
	v_pk_fma_f32 v[102:103], v[102:103], v[102:103], v[106:107]
	v_pk_fma_f32 v[100:101], v[100:101], v[100:101], v[104:105]
	v_lshlrev_b64 v[118:119], 1, v[118:119]
	v_add_f32_e32 v100, v100, v101
	v_add_f32_e32 v101, v102, v103
	v_add_f32_e32 v100, v100, v101
	v_mov_b32_e32 v101, v100
	s_nop 1
	v_permlane16_swap_b32_e32 v100, v101
	v_add_f32_e32 v100, v100, v101
	v_or_b32_e32 v118, 0x100, v118
	v_mov_b32_e32 v101, v100
	v_lshl_add_u64 v[118:119], s[10:11], 0, v[118:119]
	s_nop 0
	v_permlane32_swap_b32_e32 v100, v101
	global_store_dwordx4 v[118:119], v[108:111], off sc1
	s_and_saveexec_b64 s[26:27], s[0:1]
	s_cbranch_execz .LBB0_647
	v_lshl_add_u64 v[102:103], v[116:117], 2, s[12:13]
	v_add_f32_e32 v100, v100, v101
	global_atomic_add_f32 v[102:103], v100, off sc1
.LBB0_647:
	s_or_b64 exec, exec, s[26:27]
	v_or_b32_e32 v100, 32, v148
	v_ashrrev_i32_e32 v101, 31, v100
	v_lshlrev_b64 v[102:103], 10, v[100:101]
	v_lshl_add_u64 v[102:103], v[102:103], 0, v[2:3]
	v_lshl_add_u64 v[106:107], v[102:103], 2, s[54:55]
	global_load_dwordx4 v[108:111], v[106:107], off
	global_load_dwordx4 v[112:115], v[106:107], off offset:16
	ds_read_b32 v104, v1 offset:260
	s_and_b64 vcc, exec, s[4:5]
	s_waitcnt vmcnt(1) lgkmcnt(0)
	v_pk_fma_f32 v[98:99], v[98:99], v[104:105], v[110:111] op_sel_hi:[1,0,1]
	v_pk_fma_f32 v[96:97], v[96:97], v[104:105], v[108:109] op_sel_hi:[1,0,1]
	s_waitcnt vmcnt(0)
	v_pk_fma_f32 v[94:95], v[94:95], v[104:105], v[114:115] op_sel_hi:[1,0,1]
	v_pk_fma_f32 v[92:93], v[92:93], v[104:105], v[112:113] op_sel_hi:[1,0,1]
	s_cbranch_vccnz .LBB0_649
	v_lshl_add_u64 v[108:109], v[102:103], 2, s[28:29]
	global_store_dwordx4 v[108:109], v[96:99], off sc1
	global_store_dwordx4 v[108:109], v[92:95], off offset:16 sc1
.LBB0_649:
	v_lshl_add_u64 v[112:113], v[102:103], 1, s[10:11]
	v_cvt_pk_bf16_f32 v108, v96, v97
	v_cvt_pk_bf16_f32 v109, v98, v99
	v_cvt_pk_bf16_f32 v110, v92, v93
	v_cvt_pk_bf16_f32 v111, v94, v95
	global_store_dwordx4 v[112:113], v[108:111], off sc1
	global_load_dwordx4 v[108:111], v[106:107], off offset:512
	s_nop 0
	global_load_dwordx4 v[112:115], v[106:107], off offset:528
	v_mov_b32_e32 v105, v104
	v_mov_b32_e32 v106, v104
	v_mov_b32_e32 v107, v104
	s_and_b64 vcc, exec, s[4:5]
	s_waitcnt vmcnt(1)
	v_pk_fma_f32 v[90:91], v[90:91], v[106:107], v[110:111]
	v_pk_fma_f32 v[88:89], v[88:89], v[104:105], v[108:109]
	s_waitcnt vmcnt(0)
	v_pk_fma_f32 v[86:87], v[86:87], v[106:107], v[114:115]
	v_pk_fma_f32 v[84:85], v[84:85], v[104:105], v[112:113]
	s_cbranch_vccnz .LBB0_651
	v_lshl_add_u64 v[104:105], v[102:103], 2, s[28:29]
	global_store_dwordx4 v[104:105], v[88:91], off offset:512 sc1
	global_store_dwordx4 v[104:105], v[84:87], off offset:528 sc1
.LBB0_651:
	v_pk_mul_f32 v[94:95], v[94:95], v[94:95]
	v_pk_mul_f32 v[92:93], v[92:93], v[92:93]
	v_pk_fma_f32 v[98:99], v[98:99], v[98:99], v[94:95]
	v_pk_fma_f32 v[96:97], v[96:97], v[96:97], v[92:93]
	v_cvt_pk_bf16_f32 v92, v88, v89
	v_cvt_pk_bf16_f32 v93, v90, v91
	v_pk_fma_f32 v[90:91], v[90:91], v[90:91], v[98:99]
	v_pk_fma_f32 v[88:89], v[88:89], v[88:89], v[96:97]
	v_cvt_pk_bf16_f32 v94, v84, v85
	v_cvt_pk_bf16_f32 v95, v86, v87
	v_pk_fma_f32 v[86:87], v[86:87], v[86:87], v[90:91]
	v_pk_fma_f32 v[84:85], v[84:85], v[84:85], v[88:89]
	v_lshlrev_b64 v[102:103], 1, v[102:103]
	v_add_f32_e32 v84, v84, v85
	v_add_f32_e32 v85, v86, v87
	v_add_f32_e32 v84, v84, v85
	v_mov_b32_e32 v85, v84
	s_nop 1
	v_permlane16_swap_b32_e32 v84, v85
	v_add_f32_e32 v84, v84, v85
	v_or_b32_e32 v102, 0x100, v102
	v_mov_b32_e32 v85, v84
	v_lshl_add_u64 v[102:103], s[10:11], 0, v[102:103]
	s_nop 0
	v_permlane32_swap_b32_e32 v84, v85
	global_store_dwordx4 v[102:103], v[92:95], off sc1
	s_and_saveexec_b64 s[26:27], s[0:1]
	s_cbranch_execz .LBB0_653
	v_lshl_add_u64 v[86:87], v[100:101], 2, s[12:13]
	v_add_f32_e32 v84, v84, v85
	global_atomic_add_f32 v[86:87], v84, off sc1
.LBB0_653:
	s_or_b64 exec, exec, s[26:27]
	v_or_b32_e32 v84, 48, v148
	v_ashrrev_i32_e32 v85, 31, v84
	v_lshlrev_b64 v[86:87], 10, v[84:85]
	v_lshl_add_u64 v[86:87], v[86:87], 0, v[2:3]
	v_lshl_add_u64 v[90:91], v[86:87], 2, s[54:55]
	global_load_dwordx4 v[92:95], v[90:91], off
	global_load_dwordx4 v[96:99], v[90:91], off offset:16
	ds_read_b32 v88, v1 offset:388
	s_and_b64 vcc, exec, s[4:5]
	s_waitcnt vmcnt(1) lgkmcnt(0)
	v_pk_fma_f32 v[82:83], v[82:83], v[88:89], v[94:95] op_sel_hi:[1,0,1]
	v_pk_fma_f32 v[80:81], v[80:81], v[88:89], v[92:93] op_sel_hi:[1,0,1]
	s_waitcnt vmcnt(0)
	v_pk_fma_f32 v[78:79], v[78:79], v[88:89], v[98:99] op_sel_hi:[1,0,1]
	v_pk_fma_f32 v[76:77], v[76:77], v[88:89], v[96:97] op_sel_hi:[1,0,1]
	s_cbranch_vccnz .LBB0_655
	v_lshl_add_u64 v[92:93], v[86:87], 2, s[28:29]
	global_store_dwordx4 v[92:93], v[80:83], off sc1
	global_store_dwordx4 v[92:93], v[76:79], off offset:16 sc1
.LBB0_655:
	v_lshl_add_u64 v[96:97], v[86:87], 1, s[10:11]
	v_cvt_pk_bf16_f32 v92, v80, v81
	v_cvt_pk_bf16_f32 v93, v82, v83
	v_cvt_pk_bf16_f32 v94, v76, v77
	v_cvt_pk_bf16_f32 v95, v78, v79
	global_store_dwordx4 v[96:97], v[92:95], off sc1
	global_load_dwordx4 v[92:95], v[90:91], off offset:512
	s_nop 0
	global_load_dwordx4 v[96:99], v[90:91], off offset:528
	v_mov_b32_e32 v89, v88
	v_mov_b32_e32 v90, v88
	v_mov_b32_e32 v91, v88
	s_and_b64 vcc, exec, s[4:5]
	s_waitcnt vmcnt(1)
	v_pk_fma_f32 v[74:75], v[74:75], v[90:91], v[94:95]
	v_pk_fma_f32 v[72:73], v[72:73], v[88:89], v[92:93]
	s_waitcnt vmcnt(0)
	v_pk_fma_f32 v[70:71], v[70:71], v[90:91], v[98:99]
	v_pk_fma_f32 v[68:69], v[68:69], v[88:89], v[96:97]
	s_cbranch_vccnz .LBB0_657
	v_lshl_add_u64 v[88:89], v[86:87], 2, s[28:29]
	global_store_dwordx4 v[88:89], v[72:75], off offset:512 sc1
	global_store_dwordx4 v[88:89], v[68:71], off offset:528 sc1
.LBB0_657:
	v_pk_mul_f32 v[78:79], v[78:79], v[78:79]
	v_pk_mul_f32 v[76:77], v[76:77], v[76:77]
	v_pk_fma_f32 v[82:83], v[82:83], v[82:83], v[78:79]
	v_pk_fma_f32 v[80:81], v[80:81], v[80:81], v[76:77]
	v_cvt_pk_bf16_f32 v76, v72, v73
	v_cvt_pk_bf16_f32 v77, v74, v75
	v_pk_fma_f32 v[74:75], v[74:75], v[74:75], v[82:83]
	v_pk_fma_f32 v[72:73], v[72:73], v[72:73], v[80:81]
	v_cvt_pk_bf16_f32 v78, v68, v69
	v_cvt_pk_bf16_f32 v79, v70, v71
	v_pk_fma_f32 v[70:71], v[70:71], v[70:71], v[74:75]
	v_pk_fma_f32 v[68:69], v[68:69], v[68:69], v[72:73]
	v_lshlrev_b64 v[86:87], 1, v[86:87]
	v_add_f32_e32 v68, v68, v69
	v_add_f32_e32 v69, v70, v71
	v_add_f32_e32 v68, v68, v69
	v_mov_b32_e32 v69, v68
	s_nop 1
	v_permlane16_swap_b32_e32 v68, v69
	v_add_f32_e32 v68, v68, v69
	v_or_b32_e32 v86, 0x100, v86
	v_mov_b32_e32 v69, v68
	v_lshl_add_u64 v[86:87], s[10:11], 0, v[86:87]
	s_nop 0
	v_permlane32_swap_b32_e32 v68, v69
	global_store_dwordx4 v[86:87], v[76:79], off sc1
	s_and_saveexec_b64 s[26:27], s[0:1]
	s_cbranch_execz .LBB0_659
	v_lshl_add_u64 v[70:71], v[84:85], 2, s[12:13]
	v_add_f32_e32 v68, v68, v69
	global_atomic_add_f32 v[70:71], v68, off sc1
.LBB0_659:
	s_or_b64 exec, exec, s[26:27]
	v_add_u32_e32 v68, 0x80, v148
	v_ashrrev_i32_e32 v69, 31, v68
	v_lshlrev_b64 v[70:71], 10, v[68:69]
	v_lshl_add_u64 v[70:71], v[70:71], 0, v[2:3]
	v_lshl_add_u64 v[74:75], v[70:71], 2, s[54:55]
	global_load_dwordx4 v[76:79], v[74:75], off
	global_load_dwordx4 v[80:83], v[74:75], off offset:16
	ds_read_b32 v72, v1 offset:1028
	s_and_b64 vcc, exec, s[4:5]
	s_waitcnt vmcnt(1) lgkmcnt(0)
	v_pk_fma_f32 v[66:67], v[66:67], v[72:73], v[78:79] op_sel_hi:[1,0,1]
	v_pk_fma_f32 v[64:65], v[64:65], v[72:73], v[76:77] op_sel_hi:[1,0,1]
	s_waitcnt vmcnt(0)
	v_pk_fma_f32 v[62:63], v[62:63], v[72:73], v[82:83] op_sel_hi:[1,0,1]
	v_pk_fma_f32 v[60:61], v[60:61], v[72:73], v[80:81] op_sel_hi:[1,0,1]
	s_cbranch_vccnz .LBB0_661
	v_lshl_add_u64 v[76:77], v[70:71], 2, s[28:29]
	global_store_dwordx4 v[76:77], v[64:67], off sc1
	global_store_dwordx4 v[76:77], v[60:63], off offset:16 sc1
.LBB0_661:
	v_lshl_add_u64 v[80:81], v[70:71], 1, s[10:11]
	v_cvt_pk_bf16_f32 v76, v64, v65
	v_cvt_pk_bf16_f32 v77, v66, v67
	v_cvt_pk_bf16_f32 v78, v60, v61
	v_cvt_pk_bf16_f32 v79, v62, v63
	global_store_dwordx4 v[80:81], v[76:79], off sc1
	global_load_dwordx4 v[76:79], v[74:75], off offset:512
	s_nop 0
	global_load_dwordx4 v[80:83], v[74:75], off offset:528
	v_mov_b32_e32 v73, v72
	v_mov_b32_e32 v74, v72
	v_mov_b32_e32 v75, v72
	s_and_b64 vcc, exec, s[4:5]
	s_waitcnt vmcnt(1)
	v_pk_fma_f32 v[58:59], v[58:59], v[74:75], v[78:79]
	v_pk_fma_f32 v[56:57], v[56:57], v[72:73], v[76:77]
	s_waitcnt vmcnt(0)
	v_pk_fma_f32 v[54:55], v[54:55], v[74:75], v[82:83]
	v_pk_fma_f32 v[52:53], v[52:53], v[72:73], v[80:81]
	s_cbranch_vccnz .LBB0_663
	v_lshl_add_u64 v[72:73], v[70:71], 2, s[28:29]
	global_store_dwordx4 v[72:73], v[56:59], off offset:512 sc1
	global_store_dwordx4 v[72:73], v[52:55], off offset:528 sc1
.LBB0_663:
	v_pk_mul_f32 v[62:63], v[62:63], v[62:63]
	v_pk_mul_f32 v[60:61], v[60:61], v[60:61]
	v_pk_fma_f32 v[66:67], v[66:67], v[66:67], v[62:63]
	v_pk_fma_f32 v[64:65], v[64:65], v[64:65], v[60:61]
	v_cvt_pk_bf16_f32 v60, v56, v57
	v_cvt_pk_bf16_f32 v61, v58, v59
	v_pk_fma_f32 v[58:59], v[58:59], v[58:59], v[66:67]
	v_pk_fma_f32 v[56:57], v[56:57], v[56:57], v[64:65]
	v_cvt_pk_bf16_f32 v62, v52, v53
	v_cvt_pk_bf16_f32 v63, v54, v55
	v_pk_fma_f32 v[54:55], v[54:55], v[54:55], v[58:59]
	v_pk_fma_f32 v[52:53], v[52:53], v[52:53], v[56:57]
	v_lshlrev_b64 v[70:71], 1, v[70:71]
	v_add_f32_e32 v52, v52, v53
	v_add_f32_e32 v53, v54, v55
	v_add_f32_e32 v52, v52, v53
	v_mov_b32_e32 v53, v52
	s_nop 1
	v_permlane16_swap_b32_e32 v52, v53
	v_add_f32_e32 v52, v52, v53
	v_or_b32_e32 v70, 0x100, v70
	v_mov_b32_e32 v53, v52
	v_lshl_add_u64 v[70:71], s[10:11], 0, v[70:71]
	s_nop 0
	v_permlane32_swap_b32_e32 v52, v53
	global_store_dwordx4 v[70:71], v[60:63], off sc1
	s_and_saveexec_b64 s[26:27], s[0:1]
	s_cbranch_execz .LBB0_665
	v_lshl_add_u64 v[54:55], v[68:69], 2, s[12:13]
	v_add_f32_e32 v52, v52, v53
	global_atomic_add_f32 v[54:55], v52, off sc1
.LBB0_665:
	s_or_b64 exec, exec, s[26:27]
	v_add_u32_e32 v52, 0x90, v148
	v_ashrrev_i32_e32 v53, 31, v52
	v_lshlrev_b64 v[54:55], 10, v[52:53]
	v_lshl_add_u64 v[54:55], v[54:55], 0, v[2:3]
	v_lshl_add_u64 v[58:59], v[54:55], 2, s[54:55]
	global_load_dwordx4 v[60:63], v[58:59], off
	global_load_dwordx4 v[64:67], v[58:59], off offset:16
	ds_read_b32 v56, v1 offset:1156
	s_and_b64 vcc, exec, s[4:5]
	s_waitcnt vmcnt(1) lgkmcnt(0)
	v_pk_fma_f32 v[50:51], v[50:51], v[56:57], v[62:63] op_sel_hi:[1,0,1]
	v_pk_fma_f32 v[48:49], v[48:49], v[56:57], v[60:61] op_sel_hi:[1,0,1]
	s_waitcnt vmcnt(0)
	v_pk_fma_f32 v[46:47], v[46:47], v[56:57], v[66:67] op_sel_hi:[1,0,1]
	v_pk_fma_f32 v[44:45], v[44:45], v[56:57], v[64:65] op_sel_hi:[1,0,1]
	s_cbranch_vccnz .LBB0_667
	v_lshl_add_u64 v[60:61], v[54:55], 2, s[28:29]
	global_store_dwordx4 v[60:61], v[48:51], off sc1
	global_store_dwordx4 v[60:61], v[44:47], off offset:16 sc1
.LBB0_667:
	v_lshl_add_u64 v[64:65], v[54:55], 1, s[10:11]
	v_cvt_pk_bf16_f32 v60, v48, v49
	v_cvt_pk_bf16_f32 v61, v50, v51
	v_cvt_pk_bf16_f32 v62, v44, v45
	v_cvt_pk_bf16_f32 v63, v46, v47
	global_store_dwordx4 v[64:65], v[60:63], off sc1
	global_load_dwordx4 v[60:63], v[58:59], off offset:512
	s_nop 0
	global_load_dwordx4 v[64:67], v[58:59], off offset:528
	v_mov_b32_e32 v57, v56
	v_mov_b32_e32 v58, v56
	v_mov_b32_e32 v59, v56
	s_and_b64 vcc, exec, s[4:5]
	s_waitcnt vmcnt(1)
	v_pk_fma_f32 v[42:43], v[42:43], v[58:59], v[62:63]
	v_pk_fma_f32 v[40:41], v[40:41], v[56:57], v[60:61]
	s_waitcnt vmcnt(0)
	v_pk_fma_f32 v[38:39], v[38:39], v[58:59], v[66:67]
	v_pk_fma_f32 v[36:37], v[36:37], v[56:57], v[64:65]
	s_cbranch_vccnz .LBB0_669
	v_lshl_add_u64 v[56:57], v[54:55], 2, s[28:29]
	global_store_dwordx4 v[56:57], v[40:43], off offset:512 sc1
	global_store_dwordx4 v[56:57], v[36:39], off offset:528 sc1
.LBB0_669:
	v_pk_mul_f32 v[46:47], v[46:47], v[46:47]
	v_pk_mul_f32 v[44:45], v[44:45], v[44:45]
	v_pk_fma_f32 v[50:51], v[50:51], v[50:51], v[46:47]
	v_pk_fma_f32 v[48:49], v[48:49], v[48:49], v[44:45]
	v_cvt_pk_bf16_f32 v44, v40, v41
	v_cvt_pk_bf16_f32 v45, v42, v43
	v_pk_fma_f32 v[42:43], v[42:43], v[42:43], v[50:51]
	v_pk_fma_f32 v[40:41], v[40:41], v[40:41], v[48:49]
	v_cvt_pk_bf16_f32 v46, v36, v37
	v_cvt_pk_bf16_f32 v47, v38, v39
	v_pk_fma_f32 v[38:39], v[38:39], v[38:39], v[42:43]
	v_pk_fma_f32 v[36:37], v[36:37], v[36:37], v[40:41]
	v_lshlrev_b64 v[54:55], 1, v[54:55]
	v_add_f32_e32 v36, v36, v37
	v_add_f32_e32 v37, v38, v39
	v_add_f32_e32 v36, v36, v37
	v_mov_b32_e32 v37, v36
	s_nop 1
	v_permlane16_swap_b32_e32 v36, v37
	v_add_f32_e32 v36, v36, v37
	v_or_b32_e32 v54, 0x100, v54
	v_mov_b32_e32 v37, v36
	v_lshl_add_u64 v[54:55], s[10:11], 0, v[54:55]
	s_nop 0
	v_permlane32_swap_b32_e32 v36, v37
	global_store_dwordx4 v[54:55], v[44:47], off sc1
	s_and_saveexec_b64 s[26:27], s[0:1]
	s_cbranch_execz .LBB0_671
	v_lshl_add_u64 v[38:39], v[52:53], 2, s[12:13]
	v_add_f32_e32 v36, v36, v37
	global_atomic_add_f32 v[38:39], v36, off sc1
.LBB0_671:
	s_or_b64 exec, exec, s[26:27]
	v_add_u32_e32 v36, 0xa0, v148
	v_ashrrev_i32_e32 v37, 31, v36
	v_lshlrev_b64 v[38:39], 10, v[36:37]
	v_lshl_add_u64 v[38:39], v[38:39], 0, v[2:3]
	v_lshl_add_u64 v[42:43], v[38:39], 2, s[54:55]
	global_load_dwordx4 v[44:47], v[42:43], off
	global_load_dwordx4 v[48:51], v[42:43], off offset:16
	ds_read_b32 v40, v1 offset:1284
	s_and_b64 vcc, exec, s[4:5]
	s_waitcnt vmcnt(1) lgkmcnt(0)
	v_pk_fma_f32 v[34:35], v[34:35], v[40:41], v[46:47] op_sel_hi:[1,0,1]
	v_pk_fma_f32 v[32:33], v[32:33], v[40:41], v[44:45] op_sel_hi:[1,0,1]
	s_waitcnt vmcnt(0)
	v_pk_fma_f32 v[30:31], v[30:31], v[40:41], v[50:51] op_sel_hi:[1,0,1]
	v_pk_fma_f32 v[28:29], v[28:29], v[40:41], v[48:49] op_sel_hi:[1,0,1]
	s_cbranch_vccnz .LBB0_673
	v_lshl_add_u64 v[44:45], v[38:39], 2, s[28:29]
	global_store_dwordx4 v[44:45], v[32:35], off sc1
	global_store_dwordx4 v[44:45], v[28:31], off offset:16 sc1
.LBB0_673:
	v_lshl_add_u64 v[48:49], v[38:39], 1, s[10:11]
	v_cvt_pk_bf16_f32 v44, v32, v33
	v_cvt_pk_bf16_f32 v45, v34, v35
	v_cvt_pk_bf16_f32 v46, v28, v29
	v_cvt_pk_bf16_f32 v47, v30, v31
	global_store_dwordx4 v[48:49], v[44:47], off sc1
	global_load_dwordx4 v[44:47], v[42:43], off offset:512
	s_nop 0
	global_load_dwordx4 v[48:51], v[42:43], off offset:528
	v_mov_b32_e32 v41, v40
	v_mov_b32_e32 v42, v40
	v_mov_b32_e32 v43, v40
	s_and_b64 vcc, exec, s[4:5]
	s_waitcnt vmcnt(1)
	v_pk_fma_f32 v[26:27], v[26:27], v[42:43], v[46:47]
	v_pk_fma_f32 v[24:25], v[24:25], v[40:41], v[44:45]
	s_waitcnt vmcnt(0)
	v_pk_fma_f32 v[22:23], v[22:23], v[42:43], v[50:51]
	v_pk_fma_f32 v[20:21], v[20:21], v[40:41], v[48:49]
	s_cbranch_vccnz .LBB0_675
	v_lshl_add_u64 v[40:41], v[38:39], 2, s[28:29]
	global_store_dwordx4 v[40:41], v[24:27], off offset:512 sc1
	global_store_dwordx4 v[40:41], v[20:23], off offset:528 sc1
.LBB0_675:
	v_pk_mul_f32 v[30:31], v[30:31], v[30:31]
	v_pk_mul_f32 v[28:29], v[28:29], v[28:29]
	v_pk_fma_f32 v[34:35], v[34:35], v[34:35], v[30:31]
	v_pk_fma_f32 v[32:33], v[32:33], v[32:33], v[28:29]
	v_cvt_pk_bf16_f32 v28, v24, v25
	v_cvt_pk_bf16_f32 v29, v26, v27
	v_pk_fma_f32 v[26:27], v[26:27], v[26:27], v[34:35]
	v_pk_fma_f32 v[24:25], v[24:25], v[24:25], v[32:33]
	v_cvt_pk_bf16_f32 v30, v20, v21
	v_cvt_pk_bf16_f32 v31, v22, v23
	v_pk_fma_f32 v[22:23], v[22:23], v[22:23], v[26:27]
	v_pk_fma_f32 v[20:21], v[20:21], v[20:21], v[24:25]
	v_lshlrev_b64 v[38:39], 1, v[38:39]
	v_add_f32_e32 v20, v20, v21
	v_add_f32_e32 v21, v22, v23
	v_add_f32_e32 v20, v20, v21
	v_mov_b32_e32 v21, v20
	s_nop 1
	v_permlane16_swap_b32_e32 v20, v21
	v_add_f32_e32 v20, v20, v21
	v_or_b32_e32 v38, 0x100, v38
	v_mov_b32_e32 v21, v20
	v_lshl_add_u64 v[38:39], s[10:11], 0, v[38:39]
	s_nop 0
	v_permlane32_swap_b32_e32 v20, v21
	global_store_dwordx4 v[38:39], v[28:31], off sc1
	s_and_saveexec_b64 s[26:27], s[0:1]
	s_cbranch_execz .LBB0_677
	v_lshl_add_u64 v[22:23], v[36:37], 2, s[12:13]
	v_add_f32_e32 v20, v20, v21
	global_atomic_add_f32 v[22:23], v20, off sc1
.LBB0_677:
	s_or_b64 exec, exec, s[26:27]
	v_add_u32_e32 v20, 0xb0, v148
	v_ashrrev_i32_e32 v21, 31, v20
	v_lshlrev_b64 v[22:23], 10, v[20:21]
	v_lshl_add_u64 v[2:3], v[22:23], 0, v[2:3]
	v_lshl_add_u64 v[24:25], v[2:3], 2, s[54:55]
	global_load_dwordx4 v[26:29], v[24:25], off
	global_load_dwordx4 v[30:33], v[24:25], off offset:16
	ds_read_b32 v22, v1 offset:1412
	s_and_b64 vcc, exec, s[4:5]
	s_waitcnt vmcnt(1) lgkmcnt(0)
	v_pk_fma_f32 v[18:19], v[18:19], v[22:23], v[28:29] op_sel_hi:[1,0,1]
	v_pk_fma_f32 v[16:17], v[16:17], v[22:23], v[26:27] op_sel_hi:[1,0,1]
	s_waitcnt vmcnt(0)
	v_pk_fma_f32 v[14:15], v[14:15], v[22:23], v[32:33] op_sel_hi:[1,0,1]
	v_pk_fma_f32 v[12:13], v[12:13], v[22:23], v[30:31] op_sel_hi:[1,0,1]
	s_cbranch_vccnz .LBB0_679
	v_lshl_add_u64 v[26:27], v[2:3], 2, s[28:29]
	global_store_dwordx4 v[26:27], v[16:19], off sc1
	global_store_dwordx4 v[26:27], v[12:15], off offset:16 sc1
.LBB0_679:
	v_lshl_add_u64 v[30:31], v[2:3], 1, s[10:11]
	v_cvt_pk_bf16_f32 v26, v16, v17
	v_cvt_pk_bf16_f32 v27, v18, v19
	v_cvt_pk_bf16_f32 v28, v12, v13
	v_cvt_pk_bf16_f32 v29, v14, v15
	global_store_dwordx4 v[30:31], v[26:29], off sc1
	global_load_dwordx4 v[26:29], v[24:25], off offset:512
	s_nop 0
	global_load_dwordx4 v[30:33], v[24:25], off offset:528
	v_mov_b32_e32 v23, v22
	v_mov_b32_e32 v24, v22
	v_mov_b32_e32 v25, v22
	s_and_b64 vcc, exec, s[4:5]
	s_waitcnt vmcnt(1)
	v_pk_fma_f32 v[10:11], v[10:11], v[24:25], v[28:29]
	v_pk_fma_f32 v[8:9], v[8:9], v[22:23], v[26:27]
	s_waitcnt vmcnt(0)
	v_pk_fma_f32 v[6:7], v[6:7], v[24:25], v[32:33]
	v_pk_fma_f32 v[4:5], v[4:5], v[22:23], v[30:31]
	s_cbranch_vccnz .LBB0_681
	v_lshl_add_u64 v[22:23], v[2:3], 2, s[28:29]
	global_store_dwordx4 v[22:23], v[8:11], off offset:512 sc1
	global_store_dwordx4 v[22:23], v[4:7], off offset:528 sc1
.LBB0_681:
	v_lshlrev_b64 v[2:3], 1, v[2:3]
	v_pk_mul_f32 v[14:15], v[14:15], v[14:15]
	v_pk_mul_f32 v[12:13], v[12:13], v[12:13]
	v_or_b32_e32 v2, 0x100, v2
	v_pk_fma_f32 v[18:19], v[18:19], v[18:19], v[14:15]
	v_pk_fma_f32 v[16:17], v[16:17], v[16:17], v[12:13]
	v_lshl_add_u64 v[2:3], s[10:11], 0, v[2:3]
	v_cvt_pk_bf16_f32 v12, v8, v9
	v_cvt_pk_bf16_f32 v13, v10, v11
	v_cvt_pk_bf16_f32 v14, v4, v5
	v_cvt_pk_bf16_f32 v15, v6, v7
	global_store_dwordx4 v[2:3], v[12:15], off sc1
	v_pk_fma_f32 v[2:3], v[10:11], v[10:11], v[18:19]
	v_pk_fma_f32 v[8:9], v[8:9], v[8:9], v[16:17]
	v_pk_fma_f32 v[2:3], v[6:7], v[6:7], v[2:3]
	v_pk_fma_f32 v[4:5], v[4:5], v[4:5], v[8:9]
	v_add_f32_e32 v2, v2, v3
	v_add_f32_e32 v1, v4, v5
	v_add_f32_e32 v1, v1, v2
	v_mov_b32_e32 v2, v1
	s_nop 1
	v_permlane16_swap_b32_e32 v1, v2
	v_add_f32_e32 v1, v1, v2
	v_mov_b32_e32 v2, v1
	s_nop 1
	v_permlane32_swap_b32_e32 v1, v2
	s_and_saveexec_b64 s[4:5], s[0:1]
	s_cbranch_execz .LBB0_683
	v_lshl_add_u64 v[4:5], v[20:21], 2, s[12:13]
	v_add_f32_e32 v1, v1, v2
	global_atomic_add_f32 v[4:5], v1, off sc1

.LBB0_912:
	s_cmp_lt_i32 s89, 5
	s_cbranch_scc1 .LBB0_962
	s_waitcnt vmcnt(0)
	v_cmp_eq_u32_e32 vcc, 0, v188
	s_barrier
	s_and_saveexec_b64 s[0:1], vcc
	s_cbranch_execz .LBB0_961
	s_cmp_lg_u32 s98, 1
	s_cbranch_scc1 .Lea2_normal
	s_nop 0
	s_waitcnt vmcnt(0) lgkmcnt(0)
	v_mov_b32_e32 v0, 0x310080
	v_mov_b32_e32 v1, 1
	global_atomic_add v0, v1, s[30:31]
	v_mov_b32_e32 v0, 0x313500

.LBB0_983:
	v_lshl_add_u32 v144, s20, 8, v148
	v_ashrrev_i32_e32 v145, 31, v144
	v_lshl_add_u64 v[146:147], v[144:145], 2, s[6:7]
	v_pk_mul_f32 v[124:125], v[116:117], v[124:125]
	v_pk_mul_f32 v[158:159], v[114:115], v[122:123]
	v_pk_mul_f32 v[160:161], v[112:113], v[120:121]
	v_pk_mul_f32 v[126:127], v[118:119], v[126:127]
	v_lshl_or_b32 v156, s50, 7, v150
	v_mov_b64_e32 v[120:121], s[4:5]
	v_ashrrev_i32_e32 v157, 31, v156
	v_mad_i64_i32 v[162:163], s[22:23], v144, s49, v[120:121]
	v_or_b32_e32 v164, 16, v144
	v_lshlrev_b64 v[122:123], 1, v[156:157]
	v_ashrrev_i32_e32 v165, 31, v164
	v_lshl_add_u64 v[156:157], v[162:163], 0, v[122:123]
	v_lshl_add_u64 v[162:163], v[164:165], 2, s[6:7]
	v_pk_mul_f32 v[102:103], v[98:99], v[102:103]
	v_pk_mul_f32 v[100:101], v[96:97], v[100:101]
	v_pk_mul_f32 v[110:111], v[106:107], v[110:111]
	v_pk_mul_f32 v[108:109], v[104:105], v[108:109]
	v_pk_mul_f32 v[86:87], v[82:83], v[86:87]
	v_pk_mul_f32 v[84:85], v[80:81], v[84:85]
	v_pk_mul_f32 v[94:95], v[90:91], v[94:95]
	v_pk_mul_f32 v[92:93], v[88:89], v[92:93]
	v_pk_mul_f32 v[66:67], v[70:71], v[66:67]
	v_pk_mul_f32 v[64:65], v[68:69], v[64:65]
	v_pk_mul_f32 v[78:79], v[74:75], v[78:79]
	v_pk_mul_f32 v[76:77], v[72:73], v[76:77]
	v_pk_mul_f32 v[54:55], v[50:51], v[54:55]
	v_pk_mul_f32 v[52:53], v[48:49], v[52:53]
	v_pk_mul_f32 v[62:63], v[58:59], v[62:63]
	v_pk_mul_f32 v[60:61], v[56:57], v[60:61]
	v_pk_mul_f32 v[38:39], v[34:35], v[38:39]
	v_pk_mul_f32 v[36:37], v[32:33], v[36:37]
	v_pk_mul_f32 v[46:47], v[42:43], v[46:47]
	v_pk_mul_f32 v[44:45], v[40:41], v[44:45]
	v_pk_mul_f32 v[22:23], v[18:19], v[22:23]
	v_pk_mul_f32 v[20:21], v[16:17], v[20:21]
	v_pk_mul_f32 v[30:31], v[26:27], v[30:31]
	v_pk_mul_f32 v[28:29], v[24:25], v[28:29]
	v_pk_mul_f32 v[6:7], v[2:3], v[6:7]
	v_pk_mul_f32 v[4:5], v[0:1], v[4:5]
	v_pk_mul_f32 v[14:15], v[10:11], v[14:15]
	v_pk_mul_f32 v[12:13], v[8:9], v[12:13]
	s_andn2_b64 vcc, exec, s[0:1]
	s_mov_b64 s[0:1], -1
	s_waitcnt vmcnt(7)
	v_fmamk_f32 v145, v228, 0x3a800000, v154
	v_rsq_f32_e32 v145, v145
	s_nop 0
	v_mul_f32_e32 v166, 0xbfb8aa3b, v145
	v_pk_mul_f32 v[116:117], v[116:117], v[166:167] op_sel_hi:[1,0]
	v_pk_mul_f32 v[114:115], v[114:115], v[166:167] op_sel_hi:[1,0]
	v_pk_mul_f32 v[112:113], v[112:113], v[166:167] op_sel_hi:[1,0]
	v_pk_mul_f32 v[118:119], v[118:119], v[166:167] op_sel_hi:[1,0]
	v_exp_f32_e32 v116, v116
	v_exp_f32_e32 v117, v117
	v_exp_f32_e32 v112, v112
	v_exp_f32_e32 v114, v114
	v_exp_f32_e32 v115, v115
	v_exp_f32_e32 v113, v113
	v_exp_f32_e32 v118, v118
	v_exp_f32_e32 v119, v119
	v_pk_add_f32 v[116:117], v[116:117], 1.0 op_sel_hi:[1,0]
	v_pk_add_f32 v[114:115], v[114:115], 1.0 op_sel_hi:[1,0]
	v_pk_add_f32 v[112:113], v[112:113], 1.0 op_sel_hi:[1,0]
	v_pk_add_f32 v[118:119], v[118:119], 1.0 op_sel_hi:[1,0]
	v_rcp_f32_e32 v116, v116
	v_rcp_f32_e32 v117, v117
	v_rcp_f32_e32 v112, v112
	v_rcp_f32_e32 v114, v114
	v_rcp_f32_e32 v115, v115
	v_rcp_f32_e32 v113, v113
	v_rcp_f32_e32 v118, v118
	v_rcp_f32_e32 v119, v119
	v_mul_f32_e32 v168, v145, v145
	v_pk_mul_f32 v[124:125], v[124:125], v[168:169] op_sel_hi:[1,0]
	v_pk_mul_f32 v[160:161], v[160:161], v[168:169] op_sel_hi:[1,0]
	v_pk_mul_f32 v[158:159], v[158:159], v[168:169] op_sel_hi:[1,0]
	v_pk_mul_f32 v[126:127], v[126:127], v[168:169] op_sel_hi:[1,0]
	v_pk_mul_f32 v[116:117], v[124:125], v[116:117]
	v_pk_mul_f32 v[124:125], v[158:159], v[114:115]
	v_pk_mul_f32 v[114:115], v[160:161], v[112:113]
	v_pk_mul_f32 v[118:119], v[126:127], v[118:119]
	v_cvt_pk_bf16_f32 v112, v116, v117
	s_nop 0
	v_cvt_pk_bf16_f32 v113, v118, v119
	v_cvt_pk_bf16_f32 v114, v114, v115
	v_cvt_pk_bf16_f32 v115, v124, v125
	global_store_dwordx4 v[156:157], v[112:115], off sc1
	s_nop 0
	s_nop 0
	v_or_b32_e32 v112, 32, v144
	v_mad_i64_i32 v[114:115], s[22:23], v164, s49, v[120:121]
	v_lshl_add_u64 v[114:115], v[114:115], 0, v[122:123]
	s_waitcnt vmcnt(7)
	v_fmamk_f32 v113, v229, 0x3a800000, v154
	v_rsq_f32_e32 v119, v113
	v_ashrrev_i32_e32 v113, 31, v112
	v_lshl_add_u64 v[116:117], v[112:113], 2, s[6:7]
	v_mul_f32_e32 v118, 0xbfb8aa3b, v119
	v_pk_mul_f32 v[98:99], v[98:99], v[118:119] op_sel_hi:[1,0]
	v_pk_mul_f32 v[96:97], v[96:97], v[118:119] op_sel_hi:[1,0]
	v_pk_mul_f32 v[106:107], v[106:107], v[118:119] op_sel_hi:[1,0]
	v_pk_mul_f32 v[104:105], v[104:105], v[118:119] op_sel_hi:[1,0]
	v_exp_f32_e32 v96, v96
	v_exp_f32_e32 v98, v98
	v_exp_f32_e32 v99, v99
	v_exp_f32_e32 v97, v97
	v_exp_f32_e32 v104, v104
	v_exp_f32_e32 v105, v105
	v_exp_f32_e32 v106, v106
	v_exp_f32_e32 v107, v107
	v_pk_add_f32 v[98:99], v[98:99], 1.0 op_sel_hi:[1,0]
	v_pk_add_f32 v[96:97], v[96:97], 1.0 op_sel_hi:[1,0]
	v_pk_add_f32 v[104:105], v[104:105], 1.0 op_sel_hi:[1,0]
	v_pk_add_f32 v[106:107], v[106:107], 1.0 op_sel_hi:[1,0]
	v_rcp_f32_e32 v96, v96
	v_rcp_f32_e32 v98, v98
	v_rcp_f32_e32 v99, v99
	v_rcp_f32_e32 v97, v97
	v_rcp_f32_e32 v104, v104
	v_rcp_f32_e32 v105, v105
	v_rcp_f32_e32 v106, v106
	v_rcp_f32_e32 v107, v107
	v_mul_f32_e32 v124, v119, v119
	v_pk_mul_f32 v[100:101], v[100:101], v[124:125] op_sel_hi:[1,0]
	v_pk_mul_f32 v[102:103], v[102:103], v[124:125] op_sel_hi:[1,0]
	v_pk_mul_f32 v[108:109], v[108:109], v[124:125] op_sel_hi:[1,0]
	v_pk_mul_f32 v[110:111], v[110:111], v[124:125] op_sel_hi:[1,0]
	v_pk_mul_f32 v[102:103], v[102:103], v[98:99]
	v_pk_mul_f32 v[98:99], v[100:101], v[96:97]
	v_pk_mul_f32 v[106:107], v[110:111], v[106:107]
	v_pk_mul_f32 v[104:105], v[108:109], v[104:105]
	s_nop 0
	v_cvt_pk_bf16_f32 v96, v104, v105
	v_cvt_pk_bf16_f32 v97, v106, v107
	v_cvt_pk_bf16_f32 v98, v98, v99
	v_cvt_pk_bf16_f32 v99, v102, v103
	global_store_dwordx4 v[114:115], v[96:99], off sc1
	s_nop 0
	s_nop 0
	v_or_b32_e32 v96, 48, v144
	v_mad_i64_i32 v[98:99], s[22:23], v112, s49, v[120:121]
	v_lshl_add_u64 v[98:99], v[98:99], 0, v[122:123]
	s_waitcnt vmcnt(7)
	v_fmamk_f32 v97, v230, 0x3a800000, v154
	v_rsq_f32_e32 v103, v97
	v_ashrrev_i32_e32 v97, 31, v96
	v_lshl_add_u64 v[100:101], v[96:97], 2, s[6:7]
	v_mul_f32_e32 v102, 0xbfb8aa3b, v103
	v_pk_mul_f32 v[82:83], v[82:83], v[102:103] op_sel_hi:[1,0]
	v_pk_mul_f32 v[80:81], v[80:81], v[102:103] op_sel_hi:[1,0]
	v_pk_mul_f32 v[90:91], v[90:91], v[102:103] op_sel_hi:[1,0]
	v_pk_mul_f32 v[88:89], v[88:89], v[102:103] op_sel_hi:[1,0]
	v_exp_f32_e32 v80, v80
	v_exp_f32_e32 v82, v82
	v_exp_f32_e32 v83, v83
	v_exp_f32_e32 v81, v81
	v_exp_f32_e32 v88, v88
	v_exp_f32_e32 v89, v89
	v_exp_f32_e32 v90, v90
	v_exp_f32_e32 v91, v91
	v_pk_add_f32 v[82:83], v[82:83], 1.0 op_sel_hi:[1,0]
	v_pk_add_f32 v[80:81], v[80:81], 1.0 op_sel_hi:[1,0]
	v_pk_add_f32 v[88:89], v[88:89], 1.0 op_sel_hi:[1,0]
	v_pk_add_f32 v[90:91], v[90:91], 1.0 op_sel_hi:[1,0]
	v_rcp_f32_e32 v80, v80
	v_rcp_f32_e32 v82, v82
	v_rcp_f32_e32 v83, v83
	v_rcp_f32_e32 v81, v81
	v_rcp_f32_e32 v88, v88
	v_rcp_f32_e32 v89, v89
	v_rcp_f32_e32 v90, v90
	v_rcp_f32_e32 v91, v91
	v_mul_f32_e32 v104, v103, v103
	v_pk_mul_f32 v[84:85], v[84:85], v[104:105] op_sel_hi:[1,0]
	v_pk_mul_f32 v[86:87], v[86:87], v[104:105] op_sel_hi:[1,0]
	v_pk_mul_f32 v[92:93], v[92:93], v[104:105] op_sel_hi:[1,0]
	v_pk_mul_f32 v[94:95], v[94:95], v[104:105] op_sel_hi:[1,0]
	v_pk_mul_f32 v[86:87], v[86:87], v[82:83]
	v_pk_mul_f32 v[82:83], v[84:85], v[80:81]
	v_pk_mul_f32 v[90:91], v[94:95], v[90:91]
	v_pk_mul_f32 v[88:89], v[92:93], v[88:89]
	s_nop 0
	v_cvt_pk_bf16_f32 v80, v88, v89
	v_cvt_pk_bf16_f32 v81, v90, v91
	v_cvt_pk_bf16_f32 v82, v82, v83
	v_cvt_pk_bf16_f32 v83, v86, v87
	global_store_dwordx4 v[98:99], v[80:83], off sc1
	s_nop 0
	s_waitcnt vmcnt(7)
	v_fmamk_f32 v80, v231, 0x3a800000, v154
	v_rsq_f32_e32 v83, v80
	v_mad_i64_i32 v[80:81], s[22:23], v96, s49, v[120:121]
	v_lshl_add_u64 v[80:81], v[80:81], 0, v[122:123]
	v_mul_f32_e32 v82, 0xbfb8aa3b, v83
	v_pk_mul_f32 v[70:71], v[70:71], v[82:83] op_sel_hi:[1,0]
	v_pk_mul_f32 v[68:69], v[68:69], v[82:83] op_sel_hi:[1,0]
	v_pk_mul_f32 v[74:75], v[74:75], v[82:83] op_sel_hi:[1,0]
	v_pk_mul_f32 v[72:73], v[72:73], v[82:83] op_sel_hi:[1,0]
	v_exp_f32_e32 v68, v68
	v_exp_f32_e32 v70, v70
	v_exp_f32_e32 v71, v71
	v_exp_f32_e32 v69, v69
	v_exp_f32_e32 v72, v72
	v_exp_f32_e32 v73, v73
	v_exp_f32_e32 v74, v74
	v_exp_f32_e32 v75, v75
	v_pk_add_f32 v[70:71], v[70:71], 1.0 op_sel_hi:[1,0]
	v_pk_add_f32 v[68:69], v[68:69], 1.0 op_sel_hi:[1,0]
	v_pk_add_f32 v[72:73], v[72:73], 1.0 op_sel_hi:[1,0]
	v_pk_add_f32 v[74:75], v[74:75], 1.0 op_sel_hi:[1,0]
	v_rcp_f32_e32 v68, v68
	v_rcp_f32_e32 v70, v70
	v_rcp_f32_e32 v71, v71
	v_rcp_f32_e32 v69, v69
	v_rcp_f32_e32 v72, v72
	v_rcp_f32_e32 v73, v73
	v_rcp_f32_e32 v74, v74
	v_rcp_f32_e32 v75, v75
	v_mul_f32_e32 v84, v83, v83
	v_pk_mul_f32 v[64:65], v[64:65], v[84:85] op_sel_hi:[1,0]
	v_pk_mul_f32 v[66:67], v[66:67], v[84:85] op_sel_hi:[1,0]
	v_pk_mul_f32 v[76:77], v[76:77], v[84:85] op_sel_hi:[1,0]
	v_pk_mul_f32 v[78:79], v[78:79], v[84:85] op_sel_hi:[1,0]
	v_pk_mul_f32 v[70:71], v[66:67], v[70:71]
	v_pk_mul_f32 v[66:67], v[64:65], v[68:69]
	v_pk_mul_f32 v[74:75], v[78:79], v[74:75]
	v_pk_mul_f32 v[72:73], v[76:77], v[72:73]
	s_nop 0
	v_cvt_pk_bf16_f32 v64, v72, v73
	v_cvt_pk_bf16_f32 v65, v74, v75
	v_cvt_pk_bf16_f32 v66, v66, v67
	v_cvt_pk_bf16_f32 v67, v70, v71
	global_store_dwordx4 v[80:81], v[64:67], off sc1
	s_nop 0
	s_nop 0
	v_add_u32_e32 v65, 0x80, v144
	s_waitcnt vmcnt(7)
	v_fmamk_f32 v64, v232, 0x3a800000, v154
	v_rsq_f32_e32 v67, v64
	v_mad_i64_i32 v[64:65], s[22:23], v65, s49, v[120:121]
	v_lshl_add_u64 v[64:65], v[64:65], 0, v[122:123]
	v_mul_f32_e32 v66, 0xbfb8aa3b, v67
	v_pk_mul_f32 v[50:51], v[50:51], v[66:67] op_sel_hi:[1,0]
	v_pk_mul_f32 v[48:49], v[48:49], v[66:67] op_sel_hi:[1,0]
	v_pk_mul_f32 v[58:59], v[58:59], v[66:67] op_sel_hi:[1,0]
	v_pk_mul_f32 v[56:57], v[56:57], v[66:67] op_sel_hi:[1,0]
	v_exp_f32_e32 v48, v48
	v_exp_f32_e32 v50, v50
	v_exp_f32_e32 v51, v51
	v_exp_f32_e32 v49, v49
	v_exp_f32_e32 v56, v56
	v_exp_f32_e32 v57, v57
	v_exp_f32_e32 v58, v58
	v_exp_f32_e32 v59, v59
	v_pk_add_f32 v[50:51], v[50:51], 1.0 op_sel_hi:[1,0]
	v_pk_add_f32 v[48:49], v[48:49], 1.0 op_sel_hi:[1,0]
	v_pk_add_f32 v[56:57], v[56:57], 1.0 op_sel_hi:[1,0]
	v_pk_add_f32 v[58:59], v[58:59], 1.0 op_sel_hi:[1,0]
	v_rcp_f32_e32 v48, v48
	v_rcp_f32_e32 v50, v50
	v_rcp_f32_e32 v51, v51
	v_rcp_f32_e32 v49, v49
	v_rcp_f32_e32 v56, v56
	v_rcp_f32_e32 v57, v57
	v_rcp_f32_e32 v58, v58
	v_rcp_f32_e32 v59, v59
	v_mul_f32_e32 v68, v67, v67
	v_pk_mul_f32 v[52:53], v[52:53], v[68:69] op_sel_hi:[1,0]
	v_pk_mul_f32 v[54:55], v[54:55], v[68:69] op_sel_hi:[1,0]
	v_pk_mul_f32 v[60:61], v[60:61], v[68:69] op_sel_hi:[1,0]
	v_pk_mul_f32 v[62:63], v[62:63], v[68:69] op_sel_hi:[1,0]
	v_pk_mul_f32 v[54:55], v[54:55], v[50:51]
	v_pk_mul_f32 v[50:51], v[52:53], v[48:49]
	v_pk_mul_f32 v[58:59], v[62:63], v[58:59]
	v_pk_mul_f32 v[56:57], v[60:61], v[56:57]
	s_nop 0
	v_cvt_pk_bf16_f32 v48, v56, v57
	v_cvt_pk_bf16_f32 v49, v58, v59
	v_cvt_pk_bf16_f32 v50, v50, v51
	v_cvt_pk_bf16_f32 v51, v54, v55
	global_store_dwordx4 v[64:65], v[48:51], off sc1
	s_nop 0
	s_nop 0
	v_add_u32_e32 v49, 0x90, v144
	s_waitcnt vmcnt(7)
	v_fmamk_f32 v48, v233, 0x3a800000, v154
	v_rsq_f32_e32 v51, v48
	v_mad_i64_i32 v[48:49], s[22:23], v49, s49, v[120:121]
	v_lshl_add_u64 v[48:49], v[48:49], 0, v[122:123]
	v_mul_f32_e32 v50, 0xbfb8aa3b, v51
	v_pk_mul_f32 v[34:35], v[34:35], v[50:51] op_sel_hi:[1,0]
	v_pk_mul_f32 v[32:33], v[32:33], v[50:51] op_sel_hi:[1,0]
	v_pk_mul_f32 v[42:43], v[42:43], v[50:51] op_sel_hi:[1,0]
	v_pk_mul_f32 v[40:41], v[40:41], v[50:51] op_sel_hi:[1,0]
	v_exp_f32_e32 v32, v32
	v_exp_f32_e32 v34, v34
	v_exp_f32_e32 v35, v35
	v_exp_f32_e32 v33, v33
	v_exp_f32_e32 v40, v40
	v_exp_f32_e32 v41, v41
	v_exp_f32_e32 v42, v42
	v_exp_f32_e32 v43, v43
	v_pk_add_f32 v[34:35], v[34:35], 1.0 op_sel_hi:[1,0]
	v_pk_add_f32 v[32:33], v[32:33], 1.0 op_sel_hi:[1,0]
	v_pk_add_f32 v[40:41], v[40:41], 1.0 op_sel_hi:[1,0]
	v_pk_add_f32 v[42:43], v[42:43], 1.0 op_sel_hi:[1,0]
	v_rcp_f32_e32 v32, v32
	v_rcp_f32_e32 v34, v34
	v_rcp_f32_e32 v35, v35
	v_rcp_f32_e32 v33, v33
	v_rcp_f32_e32 v40, v40
	v_rcp_f32_e32 v41, v41
	v_rcp_f32_e32 v42, v42
	v_rcp_f32_e32 v43, v43
	v_mul_f32_e32 v52, v51, v51
	v_pk_mul_f32 v[36:37], v[36:37], v[52:53] op_sel_hi:[1,0]
	v_pk_mul_f32 v[38:39], v[38:39], v[52:53] op_sel_hi:[1,0]
	v_pk_mul_f32 v[44:45], v[44:45], v[52:53] op_sel_hi:[1,0]
	v_pk_mul_f32 v[46:47], v[46:47], v[52:53] op_sel_hi:[1,0]
	v_pk_mul_f32 v[38:39], v[38:39], v[34:35]
	v_pk_mul_f32 v[34:35], v[36:37], v[32:33]
	v_pk_mul_f32 v[42:43], v[46:47], v[42:43]
	v_pk_mul_f32 v[40:41], v[44:45], v[40:41]
	s_nop 0
	v_cvt_pk_bf16_f32 v32, v40, v41
	v_cvt_pk_bf16_f32 v33, v42, v43
	v_cvt_pk_bf16_f32 v34, v34, v35
	v_cvt_pk_bf16_f32 v35, v38, v39
	global_store_dwordx4 v[48:49], v[32:35], off sc1
	s_nop 0
	s_nop 0
	v_add_u32_e32 v33, 0xa0, v144
	s_waitcnt vmcnt(7)
	v_fmamk_f32 v32, v234, 0x3a800000, v154
	v_rsq_f32_e32 v35, v32
	v_mad_i64_i32 v[32:33], s[22:23], v33, s49, v[120:121]
	v_lshl_add_u64 v[32:33], v[32:33], 0, v[122:123]
	v_mul_f32_e32 v34, 0xbfb8aa3b, v35
	v_pk_mul_f32 v[18:19], v[18:19], v[34:35] op_sel_hi:[1,0]
	v_pk_mul_f32 v[16:17], v[16:17], v[34:35] op_sel_hi:[1,0]
	v_pk_mul_f32 v[26:27], v[26:27], v[34:35] op_sel_hi:[1,0]
	v_pk_mul_f32 v[24:25], v[24:25], v[34:35] op_sel_hi:[1,0]
	v_exp_f32_e32 v16, v16
	v_exp_f32_e32 v18, v18
	v_exp_f32_e32 v19, v19
	v_exp_f32_e32 v17, v17
	v_exp_f32_e32 v24, v24
	v_exp_f32_e32 v25, v25
	v_exp_f32_e32 v26, v26
	v_exp_f32_e32 v27, v27
	v_pk_add_f32 v[18:19], v[18:19], 1.0 op_sel_hi:[1,0]
	v_pk_add_f32 v[16:17], v[16:17], 1.0 op_sel_hi:[1,0]
	v_pk_add_f32 v[24:25], v[24:25], 1.0 op_sel_hi:[1,0]
	v_pk_add_f32 v[26:27], v[26:27], 1.0 op_sel_hi:[1,0]
	v_rcp_f32_e32 v16, v16
	v_rcp_f32_e32 v18, v18
	v_rcp_f32_e32 v19, v19
	v_rcp_f32_e32 v17, v17
	v_rcp_f32_e32 v24, v24
	v_rcp_f32_e32 v25, v25
	v_rcp_f32_e32 v26, v26
	v_rcp_f32_e32 v27, v27
	v_mul_f32_e32 v36, v35, v35
	v_pk_mul_f32 v[20:21], v[20:21], v[36:37] op_sel_hi:[1,0]
	v_pk_mul_f32 v[22:23], v[22:23], v[36:37] op_sel_hi:[1,0]
	v_pk_mul_f32 v[28:29], v[28:29], v[36:37] op_sel_hi:[1,0]
	v_pk_mul_f32 v[30:31], v[30:31], v[36:37] op_sel_hi:[1,0]
	v_pk_mul_f32 v[22:23], v[22:23], v[18:19]
	v_pk_mul_f32 v[18:19], v[20:21], v[16:17]
	v_pk_mul_f32 v[26:27], v[30:31], v[26:27]
	v_pk_mul_f32 v[24:25], v[28:29], v[24:25]
	s_nop 0
	v_cvt_pk_bf16_f32 v16, v24, v25
	v_cvt_pk_bf16_f32 v17, v26, v27
	v_cvt_pk_bf16_f32 v18, v18, v19
	v_cvt_pk_bf16_f32 v19, v22, v23
	global_store_dwordx4 v[32:33], v[16:19], off sc1
	s_nop 0
	s_nop 0
	v_add_u32_e32 v17, 0xb0, v144
	s_waitcnt vmcnt(7)
	v_fmamk_f32 v16, v235, 0x3a800000, v154
	v_rsq_f32_e32 v19, v16
	v_mad_i64_i32 v[16:17], s[22:23], v17, s49, v[120:121]
	v_lshl_add_u64 v[16:17], v[16:17], 0, v[122:123]
	v_mul_f32_e32 v18, 0xbfb8aa3b, v19
	v_pk_mul_f32 v[2:3], v[2:3], v[18:19] op_sel_hi:[1,0]
	v_pk_mul_f32 v[0:1], v[0:1], v[18:19] op_sel_hi:[1,0]
	v_pk_mul_f32 v[10:11], v[10:11], v[18:19] op_sel_hi:[1,0]
	v_pk_mul_f32 v[8:9], v[8:9], v[18:19] op_sel_hi:[1,0]
	v_exp_f32_e32 v0, v0
	v_exp_f32_e32 v2, v2
	v_exp_f32_e32 v3, v3
	v_exp_f32_e32 v1, v1
	v_exp_f32_e32 v8, v8
	v_exp_f32_e32 v9, v9
	v_exp_f32_e32 v10, v10
	v_exp_f32_e32 v11, v11
	v_pk_add_f32 v[2:3], v[2:3], 1.0 op_sel_hi:[1,0]
	v_pk_add_f32 v[0:1], v[0:1], 1.0 op_sel_hi:[1,0]
	v_pk_add_f32 v[8:9], v[8:9], 1.0 op_sel_hi:[1,0]
	v_pk_add_f32 v[10:11], v[10:11], 1.0 op_sel_hi:[1,0]
	v_rcp_f32_e32 v0, v0
	v_rcp_f32_e32 v2, v2
	v_rcp_f32_e32 v3, v3
	v_rcp_f32_e32 v1, v1
	v_rcp_f32_e32 v8, v8
	v_rcp_f32_e32 v9, v9
	v_rcp_f32_e32 v10, v10
	v_rcp_f32_e32 v11, v11
	v_mul_f32_e32 v20, v19, v19
	v_pk_mul_f32 v[4:5], v[4:5], v[20:21] op_sel_hi:[1,0]
	v_pk_mul_f32 v[6:7], v[6:7], v[20:21] op_sel_hi:[1,0]
	v_pk_mul_f32 v[12:13], v[12:13], v[20:21] op_sel_hi:[1,0]
	v_pk_mul_f32 v[14:15], v[14:15], v[20:21] op_sel_hi:[1,0]
	v_pk_mul_f32 v[6:7], v[6:7], v[2:3]
	v_pk_mul_f32 v[2:3], v[4:5], v[0:1]
	v_pk_mul_f32 v[10:11], v[14:15], v[10:11]
	v_pk_mul_f32 v[8:9], v[12:13], v[8:9]
	s_nop 0
	v_cvt_pk_bf16_f32 v0, v8, v9
	v_cvt_pk_bf16_f32 v1, v10, v11
	v_cvt_pk_bf16_f32 v2, v2, v3
	v_cvt_pk_bf16_f32 v3, v6, v7
	global_store_dwordx4 v[16:17], v[0:3], off sc1
	s_cbranch_vccnz .LBB0_972
	s_cmp_lg_u32 s42, 22
	s_cbranch_scc1 .Lea3_skip
	s_cmpk_lg_i32 s96, 0x100
	s_cbranch_scc1 .Lea3_skip
	s_waitcnt vmcnt(0) lgkmcnt(0)
	s_barrier
	s_mov_b32 s98, 1
	v_cmp_eq_u32_e32 vcc, 0, v188
	s_and_saveexec_b64 s[34:35], vcc
	s_cbranch_execz .Lea3_done
	v_mov_b32_e32 v2, 0x23fe0
	ds_read_b32 v3, v2
	ds_read_b32 v4, v2 offset:4
	v_readlane_b32 s36, v249, 20
	v_readlane_b32 s50, v249, 18
	v_readlane_b32 s51, v249, 19
	s_lshl_b32 s36, s36, 8
	s_add_u32 s36, s50, s36
	s_addc_u32 s37, s51, 0
	v_mov_b32_e32 v5, 0x1000
	v_mov_b32_e32 v6, 1
	s_nop 1
	global_atomic_add v6, v5, v6, s[36:37] offset:1024 sc0
	s_waitcnt vmcnt(0) lgkmcnt(0)
	v_add_u32_e32 v6, 1, v6
	v_lshl_add_u32 v7, v3, 2, v3
	v_cmp_eq_u32_e32 vcc, v6, v7
	s_and_saveexec_b64 s[52:53], vcc
	s_cbranch_execz .Lea3_done
	buffer_wbl2 sc1
	s_waitcnt vmcnt(0)
	v_mov_b32_e32 v5, 0x313000
	v_mov_b32_e32 v6, 1
	global_atomic_add v6, v5, v6, s[30:31] offset:1024 sc0
	s_waitcnt vmcnt(0)
	v_add_u32_e32 v6, 1, v6
	v_lshl_add_u32 v7, v4, 2, v4
	v_cmp_eq_u32_e32 vcc, v6, v7
	s_and_saveexec_b64 s[54:55], vcc
	s_cbranch_execz .Lea3_done
	v_mov_b32_e32 v5, 0x313500
	v_mov_b32_e32 v6, 1
	global_atomic_add v5, v6, s[30:31]
	s_waitcnt vmcnt(0)

.LBB0_987:
	s_cmp_lt_i32 s89, 6
	s_cbranch_scc1 .LBB0_1037
	s_waitcnt vmcnt(0)
	v_cmp_eq_u32_e32 vcc, 0, v188
	s_waitcnt vmcnt(0) lgkmcnt(0)
	s_barrier
	s_and_saveexec_b64 s[0:1], vcc
	s_cbranch_execz .LBB0_1036
	s_cmp_lg_u32 s98, 1
	s_cbranch_scc1 .Lea3_normal
	s_nop 0
	s_waitcnt vmcnt(0) lgkmcnt(0)
	v_mov_b32_e32 v0, 0x3100c0
	v_mov_b32_e32 v1, 1
	global_atomic_add v0, v1, s[30:31]
	v_mov_b32_e32 v0, 0x313500
